# P1 qkv GEMM: staggered (non-aligned) epilogues instead of aligned; plus deferred queue-atomic wait
# speedup vs baseline: 1.0002x; 1.0002x over previous
; __device__ __forceinline__ int lane_id() { int l; asm volatile("v_mbcnt_lo_u32_b32 %0, -1, 0\n\tv_mbcnt_hi_u32_b32 %0, -1, %0" : "=v"(l)); return l; }
; __device__ __forceinline__ unsigned pk2(float lo, float hi) { f32x2_t v = {lo, hi}; bf16x2_t b = __builtin_convertvector(v, bf16x2_t); return __builtin_bit_cast(unsigned, b); }
; #define PG8_BAR __builtin_amdgcn_s_barrier()
;     __device__ __forceinline__ void operator()(const f32x4 (&acc)[2][2][4][2], const Unit& u, int wr, int wc, int fr, int fq) const {
;     ...
;         const int row0 = u.pm * BM + wr * 64 + fr, col0 = u.pn * BM + wc * 32 + 8 * fq;
; #pragma unroll
;         for (int ai = 0; ai < 2; ++ai)
; #pragma unroll
;             for (int m = 0; m < 4; ++m) { bf16_t* rowp = O + (size_t)(row0 + ai * HALF + m * 16) * ldc + col0;
; #pragma unroll
;                 for (int bj = 0; bj < 2; ++bj) { const f32x4 v0 = acc[ai][bj][m][0] * sc, v1 = acc[ai][bj][m][1] * sc;
;                     u32x4 w; w.x = pk2(v0[0], v0[1]); w.y = pk2(v0[2], v0[3]); w.z = pk2(v1[0], v1[1]); w.w = pk2(v1[2], v1[3]);
;                     *(u32x4*)(rowp + bj * HALF) = w; } }
; template <class Epi, class SchedT, bool ALIGN_EPI, bool SP2, bool FP8 = false>
; __device__ __forceinline__ void gemm_phase(LAS unsigned char* lds, const Gemm g, const SchedT& S, const Epi& E, const int wid) {
;     ...
;         if constexpr (ALIGN_EPI) { if (wr == 0) PG8_BAR; }
;         { const int l2_ = lane_id(); E(acc, cur, wr, wc, l2_ & 15, l2_ >> 4); }
;         if (!has_next) break;
; #pragma unroll
;         for (int a = 0; a < 2; ++a)
; #pragma unroll
;             for (int b = 0; b < 2; ++b)
; #pragma unroll
;                 for (int m = 0; m < 4; ++m)
; #pragma unroll
;                     for (int n = 0; n < 2; ++n) acc[a][b][m][n] = (f32x4){0.f, 0.f, 0.f, 0.f};
;         cur = nxt; cA = nA; cB = nB; ++ui;
;         if constexpr (ALIGN_EPI) { if (wr == 1) PG8_BAR; }
.LBB0_241:
.LBB0_242:
	v_mbcnt_lo_u32_b32 v16, -1, 0
	v_mbcnt_hi_u32_b32 v16, -1, v16
	s_lshl_b32 s7, s44, 8
	v_and_b32_e32 v17, 15, v16
	v_ashrrev_i32_e32 v16, 4, v16
	s_lshl_b32 s6, s43, 8
	s_or_b32 s7, s7, s78
	v_lshl_add_u32 v16, v16, 3, s7
	s_add_i32 s6, s6, s91
	v_add_u32_e32 v128, s6, v17
	v_ashrrev_i32_e32 v17, 31, v16
	v_mov_b64_e32 v[24:25], s[2:3]
	v_mad_i64_i32 v[18:19], s[8:9], v128, s34, v[24:25]
	v_lshlrev_b64 v[26:27], 1, v[16:17]
	v_lshl_add_u64 v[148:149], v[18:19], 0, v[26:27]
	v_cvt_pk_bf16_f32 v16, v124, v125
	v_cvt_pk_bf16_f32 v17, v126, v127
	v_cvt_pk_bf16_f32 v18, v120, v121
	v_cvt_pk_bf16_f32 v19, v122, v123
	global_store_dwordx4 v[148:149], v[16:19], off
	v_cvt_pk_bf16_f32 v4, v4, v5
	v_cvt_pk_bf16_f32 v5, v6, v7
	v_cvt_pk_bf16_f32 v16, v132, v133
	v_cvt_pk_bf16_f32 v17, v130, v131
	v_cvt_pk_bf16_f32 v18, v136, v137
	v_cvt_pk_bf16_f32 v19, v134, v135
	global_store_dwordx4 v[148:149], v[16:19], off offset:256
	v_cvt_pk_bf16_f32 v6, v0, v1
	v_cvt_pk_bf16_f32 v7, v2, v3
	v_add_u32_e32 v16, 16, v128
	v_mad_i64_i32 v[16:17], s[8:9], v16, s34, v[24:25]
	v_lshl_add_u64 v[120:121], v[16:17], 0, v[26:27]
	v_cvt_pk_bf16_f32 v16, v102, v103
	v_cvt_pk_bf16_f32 v17, v100, v101
	v_cvt_pk_bf16_f32 v18, v110, v111
	v_cvt_pk_bf16_f32 v19, v108, v109
	global_store_dwordx4 v[120:121], v[16:19], off
	s_and_b64 vcc, exec, s[0:1]
	s_mov_b64 s[0:1], -1
	v_cvt_pk_bf16_f32 v16, v114, v115
	v_cvt_pk_bf16_f32 v17, v112, v113
	v_cvt_pk_bf16_f32 v18, v118, v119
	v_cvt_pk_bf16_f32 v19, v116, v117
	global_store_dwordx4 v[120:121], v[16:19], off offset:256
	s_nop 1
	v_add_u32_e32 v16, 32, v128
	v_mad_i64_i32 v[16:17], s[8:9], v16, s34, v[24:25]
	v_lshl_add_u64 v[100:101], v[16:17], 0, v[26:27]
	v_cvt_pk_bf16_f32 v16, v86, v87
	v_cvt_pk_bf16_f32 v17, v84, v85
	v_cvt_pk_bf16_f32 v18, v94, v95
	v_cvt_pk_bf16_f32 v19, v92, v93
	global_store_dwordx4 v[100:101], v[16:19], off
	s_nop 1
	v_cvt_pk_bf16_f32 v16, v98, v99
	v_cvt_pk_bf16_f32 v17, v96, v97
	v_cvt_pk_bf16_f32 v18, v106, v107
	v_cvt_pk_bf16_f32 v19, v104, v105
	global_store_dwordx4 v[100:101], v[16:19], off offset:256
	s_nop 1
	v_add_u32_e32 v16, 48, v128
	v_mad_i64_i32 v[16:17], s[8:9], v16, s34, v[24:25]
	v_lshl_add_u64 v[84:85], v[16:17], 0, v[26:27]
	v_cvt_pk_bf16_f32 v16, v74, v75
	v_cvt_pk_bf16_f32 v17, v72, v73
	v_cvt_pk_bf16_f32 v18, v78, v79
	v_cvt_pk_bf16_f32 v19, v76, v77
	global_store_dwordx4 v[84:85], v[16:19], off
	s_nop 1
	v_cvt_pk_bf16_f32 v16, v68, v69
	v_cvt_pk_bf16_f32 v17, v70, v71
	v_cvt_pk_bf16_f32 v18, v80, v81
	v_cvt_pk_bf16_f32 v19, v62, v63
	global_store_dwordx4 v[84:85], v[16:19], off offset:256
	s_nop 1
	v_add_u32_e32 v16, 0x80, v128
	v_mad_i64_i32 v[16:17], s[8:9], v16, s34, v[24:25]
	v_lshl_add_u64 v[62:63], v[16:17], 0, v[26:27]
	v_cvt_pk_bf16_f32 v16, v64, v65
	v_cvt_pk_bf16_f32 v17, v60, v61
	v_cvt_pk_bf16_f32 v18, v56, v57
	v_cvt_pk_bf16_f32 v19, v58, v59
	global_store_dwordx4 v[62:63], v[16:19], off
	s_nop 1
	v_cvt_pk_bf16_f32 v16, v82, v83
	v_cvt_pk_bf16_f32 v17, v66, v67
	v_cvt_pk_bf16_f32 v18, v90, v91
	v_cvt_pk_bf16_f32 v19, v88, v89
	global_store_dwordx4 v[62:63], v[16:19], off offset:256
	s_nop 1
	v_add_u32_e32 v16, 0x90, v128
	v_mad_i64_i32 v[16:17], s[8:9], v16, s34, v[24:25]
	v_lshl_add_u64 v[56:57], v[16:17], 0, v[26:27]
	v_cvt_pk_bf16_f32 v16, v38, v39
	v_cvt_pk_bf16_f32 v17, v36, v37
	v_cvt_pk_bf16_f32 v18, v46, v47
	v_cvt_pk_bf16_f32 v19, v44, v45
	global_store_dwordx4 v[56:57], v[16:19], off
	s_nop 1
	v_cvt_pk_bf16_f32 v16, v50, v51
	v_cvt_pk_bf16_f32 v17, v48, v49
	v_cvt_pk_bf16_f32 v18, v54, v55
	v_cvt_pk_bf16_f32 v19, v52, v53
	global_store_dwordx4 v[56:57], v[16:19], off offset:256
	s_nop 1
	v_add_u32_e32 v16, 0xa0, v128
	v_mad_i64_i32 v[16:17], s[8:9], v16, s34, v[24:25]
	v_lshl_add_u64 v[36:37], v[16:17], 0, v[26:27]
	v_cvt_pk_bf16_f32 v16, v22, v23
	v_cvt_pk_bf16_f32 v17, v20, v21
	v_cvt_pk_bf16_f32 v18, v30, v31
	v_cvt_pk_bf16_f32 v19, v28, v29
	global_store_dwordx4 v[36:37], v[16:19], off
	s_nop 1
	v_cvt_pk_bf16_f32 v16, v34, v35
	v_cvt_pk_bf16_f32 v17, v32, v33
	v_cvt_pk_bf16_f32 v18, v42, v43
	v_cvt_pk_bf16_f32 v19, v40, v41
	global_store_dwordx4 v[36:37], v[16:19], off offset:256
	s_nop 1
	v_add_u32_e32 v16, 0xb0, v128
	v_mad_i64_i32 v[16:17], s[8:9], v16, s34, v[24:25]
	v_lshl_add_u64 v[20:21], v[16:17], 0, v[26:27]
	v_cvt_pk_bf16_f32 v16, v10, v11
	v_cvt_pk_bf16_f32 v17, v8, v9
	v_cvt_pk_bf16_f32 v18, v14, v15
	v_cvt_pk_bf16_f32 v19, v12, v13
	global_store_dwordx4 v[20:21], v[16:19], off
	global_store_dwordx4 v[20:21], v[4:7], off offset:256
	s_cbranch_vccnz .LBB0_226
	v_readlane_b32 s0, v248, 1
	v_readlane_b32 s1, v248, 2
	s_andn2_b64 vcc, exec, s[0:1]
	s_cbranch_vccnz .LBB0_225
	s_branch .LBB0_225

; #define PG8_WAIT_V(n) asm volatile("s_waitcnt vmcnt(" #n ")" ::: "memory")
; #define PG8_BAR __builtin_amdgcn_s_barrier()
; template <class Epi, class SchedT, bool ALIGN_EPI, bool SP2, bool FP8 = false>
; __device__ __forceinline__ void gemm_phase(LAS unsigned char* lds, const Gemm g, const SchedT& S, const Epi& E, const int wid) {
;     ...
;     PG8_WAIT_V(0);
;     if constexpr (!ALIGN_EPI) { if (wr == 0) PG8_BAR; }
;     PG8_BAR;
.LBB0_246:
	s_and_b64 vcc, exec, s[96:97]
	s_cbranch_vccz .Lp1_na_skip
	s_barrier
